# MLA attention loop: 4-slot V ring in LDS (XOR-rotated addresses) so the mid-tile barrier is dropped: one workgroup barrier per key tile instead of two
# speedup vs baseline: 1.0101x; 1.0044x over previous
; #define SLOAD(i, k0) do { st_[i].vs = *reinterpret_cast<const bf16x8*>(&Vh[(size_t)((k0) + sr) * LDK + sc]); \
;     st_[i].ks = *reinterpret_cast<const bf16x8*>(&Kh[(size_t)((k0) + sr) * LDK + sc]); \
;     if (DQ == 96) st_[i].kr = *reinterpret_cast<const bf16x8*>(&Kr[(size_t)((k0) + sr2) * 32 + sc2]); } while (0)
; #define SWRITE(b, i) do { *(bf16x8*)(V_lds + (b) * SHM_V + vst0) = st_[i].vs; *(bf16x8*)(K_lds + (b) * SHM_K + kst0) = st_[i].ks; \
;     if (DQ == 96) { if (tid < 256) *(bf16x8*)(K_lds + (b) * SHM_K + kst2) = st_[i].kr; } } while (0)
; #define SWAIT() do { if (DQ == 96) asm volatile("s_waitcnt vmcnt(3)" ::: "memory"); else asm volatile("s_waitcnt vmcnt(2)" ::: "memory"); } while (0)
; #define SLOAD(i, k0) do { st_[i].vs = *reinterpret_cast<const bf16x8*>(&Vh[(size_t)((k0) + sr) * LDK + sc]); \
;     st_[i].ks = *reinterpret_cast<const bf16x8*>(&Kh[(size_t)((k0) + sr) * LDK + sc]); \
;     if (DQ == 96) st_[i].kr = *reinterpret_cast<const bf16x8*>(&Kr[(size_t)((k0) + sr2) * 32 + sc2]); } while (0)
; #define SWRITE(b, i) do { *(bf16x8*)(V_lds + (b) * SHM_V + vst0) = st_[i].vs; *(bf16x8*)(K_lds + (b) * SHM_K + kst0) = st_[i].ks; \
;     if (DQ == 96) { if (tid < 256) *(bf16x8*)(K_lds + (b) * SHM_K + kst2) = st_[i].kr; } } while (0)
; __device__ __forceinline__ float row_max32(const f32x16& p0, const f32x16& p1) {
;     float pmax = p0[0];
; #pragma unroll
;     for (int r = 1; r < 16; ++r) pmax = fmaxf(pmax, p0[r]);
; #pragma unroll
;     for (int r = 0; r < 16; ++r) pmax = fmaxf(pmax, p1[r]);
;     auto rr = __builtin_amdgcn_permlane32_swap(__float_as_uint(pmax), __float_as_uint(pmax), false, false);
;     return fmaxf(__uint_as_float(rr[0]), __uint_as_float(rr[1]));
; }
; template <int DQ, bool WIN, int LDQ, int LDK> ...
;     ...
;     SLOAD(SE, KBASE(0)); SLOAD(SO, KBASE(1));
;     SWAIT(); SWRITE(0, SE); __syncthreads();
;     qkt<DQ>(pA0, pA1, K_lds, qr, zero16, r32, hi);
;     if (WIN) win_mask(pA0, pA1, qrow - KBASE(0), hi);
;     { const float pm = row_max32(pA0, pA1); m_ref = (pm > -1e37f) ? pm : 0.f;
; #pragma unroll
;       for (int r = 0; r < 16; ++r) { minit[r] = -m_ref; pA0[r] -= m_ref; pA1[r] -= m_ref; } }
;     exp16(pA0);
;     if (2 < NT) SLOAD(SE, KBASE(2));
;     SWAIT(); SWRITE(1, SO); __syncthreads();
.LBB0_1088:
	s_or_b64 exec, exec, s[16:17]
	v_and_b32_e32 v188, 31, v80
	s_movk_i32 s16, 0xd0
	v_mad_u32_u24 v0, v188, s16, 0
	v_add_u32_e32 v191, v0, v112
	s_waitcnt lgkmcnt(0)
	s_barrier
	ds_read_b128 v[0:3], v191 offset:16384
	ds_read_b128 v[52:55], v191 offset:16416
	s_waitcnt lgkmcnt(1)
	v_mfma_f32_32x32x16_bf16 v[16:31], v[0:3], v[134:137], 0
	ds_read_b128 v[0:3], v191 offset:23040
	ds_read_b128 v[56:59], v191 offset:23072
	v_lshl_or_b32 v50, v50, 1, v44
	v_mov_b32_e32 v51, v45
	v_lshl_add_u64 v[50:51], s[6:7], 0, v[50:51]
	s_mov_b64 s[16:17], 0x80000
	s_waitcnt lgkmcnt(1)
	v_mfma_f32_32x32x16_bf16 v[0:15], v[0:3], v[134:137], 0
	v_mfma_f32_32x32x16_bf16 v[16:31], v[52:55], v[130:133], v[16:31]
	s_waitcnt lgkmcnt(0)
	v_mfma_f32_32x32x16_bf16 v[0:15], v[56:59], v[130:133], v[0:15]
	ds_read_b128 v[52:55], v191 offset:16448
	ds_read_b128 v[56:59], v191 offset:16480
	s_waitcnt lgkmcnt(1)
	v_mfma_f32_32x32x16_bf16 v[16:31], v[52:55], v[126:129], v[16:31]
	ds_read_b128 v[52:55], v191 offset:23104
	ds_read_b128 v[60:63], v191 offset:23136
	s_waitcnt lgkmcnt(2)
	v_mfma_f32_32x32x16_bf16 v[16:31], v[56:59], v[122:125], v[16:31]
	v_lshl_add_u64 v[56:57], v[50:51], 0, s[16:17]
	v_add_co_u32_e32 v50, vcc, 0x80000, v50
	s_mov_b32 s16, 0xfcf0bdc2
	s_nop 0
	v_addc_co_u32_e32 v51, vcc, 0, v51, vcc
	v_add_co_u32_e32 v46, vcc, 0x2000, v46
	s_waitcnt lgkmcnt(1)
	v_mfma_f32_32x32x16_bf16 v[0:15], v[52:55], v[126:129], v[0:15]
	v_addc_co_u32_e32 v47, vcc, 0, v47, vcc
	ds_read_b128 v[52:55], v191 offset:16512
	ds_read_b128 v[64:67], v191 offset:16544
	global_load_dwordx4 v[138:141], v[56:57], off offset:128
	global_load_dwordx4 v[142:145], v[50:51], off
	global_load_dwordx4 v[146:149], v[46:47], off
	s_waitcnt lgkmcnt(1)
	v_mfma_f32_32x32x16_bf16 v[16:31], v[52:55], v[118:121], v[16:31]
	ds_read_b128 v[50:53], v191 offset:23168
	ds_read_b128 v[54:57], v191 offset:23200
	s_waitcnt vmcnt(3)
	ds_write_b128 v192, v[36:39] offset:8192
	ds_write_b128 v193, v[40:43] offset:29696
	v_add_u32_e32 v36, v48, v49
	v_mfma_f32_32x32x16_bf16 v[0:15], v[60:63], v[122:125], v[0:15]
	s_waitcnt lgkmcnt(4)
	v_mfma_f32_32x32x16_bf16 v[16:31], v[64:67], v[114:117], v[16:31]
	s_waitcnt lgkmcnt(3)
	v_mfma_f32_32x32x16_bf16 v[0:15], v[50:53], v[118:121], v[0:15]
	s_nop 9
	v_max_f32_e32 v46, v17, v17
	v_max_f32_e32 v47, v16, v16
	v_max_f32_e32 v46, v47, v46
	v_max3_f32 v46, v46, v18, v19
	v_max3_f32 v46, v46, v20, v21
	v_max3_f32 v46, v46, v22, v23
	v_max3_f32 v46, v46, v24, v25
	s_waitcnt lgkmcnt(2)
	v_mfma_f32_32x32x16_bf16 v[0:15], v[54:57], v[114:117], v[0:15]
	v_max3_f32 v46, v46, v26, v27
	v_max3_f32 v46, v46, v28, v29
	v_max3_f32 v46, v46, v30, v31
	s_nop 8
	v_max3_f32 v46, v46, v0, v1
	v_max3_f32 v46, v46, v2, v3
	v_max3_f32 v46, v46, v4, v5
	v_max3_f32 v46, v46, v6, v7
	v_max3_f32 v46, v46, v8, v9
	v_max3_f32 v46, v46, v10, v11
	v_max3_f32 v46, v46, v12, v13
	v_max3_f32 v46, v46, v14, v15
	v_mov_b32_e32 v47, v46
	s_nop 1
	v_permlane32_swap_b32_e32 v46, v47
	v_max_f32_e32 v47, v47, v47
	v_max_f32_e32 v46, v46, v46
	v_max_f32_e32 v46, v46, v47
	v_cmp_lt_f32_e32 vcc, s16, v46
	s_and_saveexec_b64 s[16:17], s[4:5]
	s_xor_b64 s[4:5], exec, s[16:17]
	v_add_u32_e32 v36, v48, v49
	s_andn2_saveexec_b64 s[4:5], s[4:5]
	v_add_u32_e32 v37, 0, v36
	ds_write_b128 v37, v[32:35] offset:29824
	s_or_b64 exec, exec, s[4:5]
	v_and_b32_e32 v189, 63, v80
	v_cndmask_b32_e32 v32, 0, v46, vcc
	v_sub_f32_e32 v65, v1, v32
	v_lshlrev_b32_e32 v1, 4, v189
	s_lshr_b32 s4, s20, 5
	s_and_b32 s16, s18, 0xffffffe0
	v_sub_f32_e32 v66, v2, v32
	v_sub_f32_e32 v64, v0, v32
	v_lshlrev_b32_e32 v0, 3, v189
	v_and_b32_e32 v1, 0xc0, v1
	v_lshlrev_b32_e32 v2, 1, v189
	v_and_or_b32 v1, v0, 24, v1
	v_and_b32_e32 v2, 32, v2
	v_and_b32_e32 v0, 0x100, v0
	s_cmp_lg_u32 0, -1
	v_or3_b32 v0, v1, v2, v0
	s_cselect_b32 s5, 0, 0
	s_and_b32 s4, s4, 15
	v_add_u32_e32 v194, s5, v0
	s_lshl_b32 s21, s4, 8
	s_addk_i32 s5, 0x2000
	s_add_u32 s10, s10, 0x10800000
	s_addc_u32 s11, s11, 0
	v_sub_f32_e32 v16, v16, v32
	v_sub_f32_e32 v17, v17, v32
	v_sub_f32_e32 v18, v18, v32
	v_sub_f32_e32 v19, v19, v32
	v_sub_f32_e32 v20, v20, v32
	v_sub_f32_e32 v21, v21, v32
	v_sub_f32_e32 v22, v22, v32
	v_sub_f32_e32 v23, v23, v32
	v_sub_f32_e32 v24, v24, v32
	v_sub_f32_e32 v25, v25, v32
	v_sub_f32_e32 v26, v26, v32
	v_sub_f32_e32 v27, v27, v32
	v_sub_f32_e32 v28, v28, v32
	v_sub_f32_e32 v29, v29, v32
	v_sub_f32_e32 v30, v30, v32
	v_sub_f32_e32 v31, v31, v32
	v_add_lshl_u32 v2, v82, v81, 1
	s_add_u32 s4, s21, s0
	v_exp_f32_e32 v161, v16
	v_exp_f32_e32 v196, v17
	v_exp_f32_e32 v158, v18
	v_exp_f32_e32 v168, v19
	v_exp_f32_e32 v159, v20
	v_exp_f32_e32 v169, v21
	v_exp_f32_e32 v160, v22
	v_exp_f32_e32 v195, v23
	v_exp_f32_e32 v150, v24
	v_exp_f32_e32 v154, v25
	v_exp_f32_e32 v151, v26
	v_exp_f32_e32 v155, v27
	v_exp_f32_e32 v152, v28
	v_exp_f32_e32 v156, v29
	v_exp_f32_e32 v153, v30
	v_exp_f32_e32 v157, v31
	v_sub_f32_e32 v67, v3, v32
	v_add_u32_e32 v190, s5, v0
	v_or_b32_e32 v112, 0x4000, v2
	s_addc_u32 s5, 0, s1
	v_and_b32_e32 v3, 7, v80
	v_lshl_add_u64 v[162:163], s[10:11], 0, v[112:113]
	v_lshl_add_u64 v[0:1], s[4:5], 0, v[44:45]
	v_lshlrev_b32_e32 v112, 4, v3
	v_xor_b32_e32 v48, 0x80000000, v32
	v_lshl_add_u64 v[164:165], v[0:1], 0, v[112:113]
	v_add_u32_e32 v112, 0x3000, v2
	v_mov_b32_e32 v0, 0
	v_mov_b32_e32 v49, v48
	v_mov_b32_e32 v50, v48
	v_mov_b32_e32 v51, v48
	v_mov_b32_e32 v52, v48
	v_mov_b32_e32 v53, v48
	v_mov_b32_e32 v54, v48
	v_mov_b32_e32 v55, v48
	v_mov_b32_e32 v56, v48
	v_mov_b32_e32 v57, v48
	v_mov_b32_e32 v58, v48
	v_mov_b32_e32 v59, v48
	v_mov_b32_e32 v60, v48
	v_mov_b32_e32 v61, v48
	v_mov_b32_e32 v62, v48
	v_mov_b32_e32 v63, v48
; #define SBAR() __builtin_amdgcn_sched_barrier(0)
; #define SLOAD(i, k0) do { st_[i].vs = *reinterpret_cast<const bf16x8*>(&Vh[(size_t)((k0) + sr) * LDK + sc]); \
;     st_[i].ks = *reinterpret_cast<const bf16x8*>(&Kh[(size_t)((k0) + sr) * LDK + sc]); \
;     if (DQ == 96) st_[i].kr = *reinterpret_cast<const bf16x8*>(&Kr[(size_t)((k0) + sr2) * 32 + sc2]); } while (0)
; #define SWRITE(b, i) do { *(bf16x8*)(V_lds + (b) * SHM_V + vst0) = st_[i].vs; *(bf16x8*)(K_lds + (b) * SHM_K + kst0) = st_[i].ks; \
;     if (DQ == 96) { if (tid < 256) *(bf16x8*)(K_lds + (b) * SHM_K + kst2) = st_[i].kr; } } while (0)
; #define SWAIT() do { if (DQ == 96) asm volatile("s_waitcnt vmcnt(3)" ::: "memory"); else asm volatile("s_waitcnt vmcnt(2)" ::: "memory"); } while (0)
; #define SLOAD(i, k0) do { st_[i].vs = *reinterpret_cast<const bf16x8*>(&Vh[(size_t)((k0) + sr) * LDK + sc]); \
;     st_[i].ks = *reinterpret_cast<const bf16x8*>(&Kh[(size_t)((k0) + sr) * LDK + sc]); \
;     if (DQ == 96) st_[i].kr = *reinterpret_cast<const bf16x8*>(&Kr[(size_t)((k0) + sr2) * 32 + sc2]); } while (0)
; #define SWRITE(b, i) do { *(bf16x8*)(V_lds + (b) * SHM_V + vst0) = st_[i].vs; *(bf16x8*)(K_lds + (b) * SHM_K + kst0) = st_[i].ks; \
;     if (DQ == 96) { if (tid < 256) *(bf16x8*)(K_lds + (b) * SHM_K + kst2) = st_[i].kr; } } while (0)
; #define SWAIT() do { if (DQ == 96) asm volatile("s_waitcnt vmcnt(3)" ::: "memory"); else asm volatile("s_waitcnt vmcnt(2)" ::: "memory"); } while (0)
; template <int DQ, bool WIN, int LDQ, int LDK> ...
;     ...
;     auto lsum_upd = [&]() {
;         lsum = __builtin_amdgcn_mfma_f32_32x32x16_bf16(pa0, ones8, lsum, 0, 0, 0);
;         lsum = __builtin_amdgcn_mfma_f32_32x32x16_bf16(pa1, ones8, lsum, 0, 0, 0);
;         lsum = __builtin_amdgcn_mfma_f32_32x32x16_bf16(pa2, ones8, lsum, 0, 0, 0);
;         lsum = __builtin_amdgcn_mfma_f32_32x32x16_bf16(pa3, ones8, lsum, 0, 0, 0);
;     };
;     ...
;     { const float pm = row_max32(pA0, pA1); m_ref = (pm > -1e37f) ? pm : 0.f;
; #pragma unroll
;       for (int r = 0; r < 16; ++r) { minit[r] = -m_ref; pA0[r] -= m_ref; pA1[r] -= m_ref; } }
;     exp16(pA0);
;     if (2 < NT) SLOAD(SE, KBASE(2));
;     SWAIT(); SWRITE(1, SO); __syncthreads();
; #pragma unroll 1
;     for (int j = 1; j + 1 < NT; j += 2) {
;         SBAR(); qkt<DQ>(pB0, pB1, K_lds + SHM_K, qr, minit, r32, hi);
;         finish(pA0, pA1); SBAR();
	v_sub_f32_e32 v79, v15, v32
	v_sub_f32_e32 v78, v14, v32
	v_sub_f32_e32 v77, v13, v32
	v_sub_f32_e32 v76, v12, v32
	v_sub_f32_e32 v75, v11, v32
	v_sub_f32_e32 v74, v10, v32
	v_sub_f32_e32 v73, v9, v32
	v_sub_f32_e32 v72, v8, v32
	v_sub_f32_e32 v71, v7, v32
	v_sub_f32_e32 v70, v6, v32
	v_sub_f32_e32 v69, v5, v32
	v_sub_f32_e32 v68, v4, v32
	s_mov_b32 s17, -1
	v_lshl_add_u64 v[166:167], s[10:11], 0, v[112:113]
	v_add_u32_e32 v112, 0, v36
	v_mov_b32_e32 v1, v0
	v_mov_b32_e32 v2, v0
	v_mov_b32_e32 v3, v0
	v_mov_b32_e32 v4, v0
	v_mov_b32_e32 v5, v0
	v_mov_b32_e32 v6, v0
	v_mov_b32_e32 v7, v0
	v_mov_b32_e32 v8, v0
	v_mov_b32_e32 v9, v0
	v_mov_b32_e32 v10, v0
	v_mov_b32_e32 v11, v0
	v_mov_b32_e32 v12, v0
	v_mov_b32_e32 v13, v0
	v_mov_b32_e32 v14, v0
	v_mov_b32_e32 v15, v0
	v_mov_b32_e32 v16, v0
	v_mov_b32_e32 v17, v0
	v_mov_b32_e32 v18, v0
	v_mov_b32_e32 v19, v0
	v_mov_b32_e32 v20, v0
	v_mov_b32_e32 v21, v0
	v_mov_b32_e32 v22, v0
	v_mov_b32_e32 v23, v0
	v_mov_b32_e32 v24, v0
	v_mov_b32_e32 v25, v0
	v_mov_b32_e32 v26, v0
	v_mov_b32_e32 v27, v0
	v_mov_b32_e32 v28, v0
	v_mov_b32_e32 v29, v0
	v_mov_b32_e32 v30, v0
	v_mov_b32_e32 v31, v0
	v_mov_b32_e32 v32, v0
	v_mov_b32_e32 v33, v0
	v_mov_b32_e32 v34, v0
	v_mov_b32_e32 v35, v0
	v_mov_b32_e32 v36, v0
	v_mov_b32_e32 v37, v0
	v_mov_b32_e32 v38, v0
	v_mov_b32_e32 v39, v0
	v_mov_b32_e32 v40, v0
	v_mov_b32_e32 v41, v0
	v_mov_b32_e32 v42, v0
	v_mov_b32_e32 v43, v0
	v_mov_b32_e32 v44, v0
	v_mov_b32_e32 v45, v0
	v_mov_b32_e32 v46, v0
	v_mov_b32_e32 v47, v0
	v_xor_b32_e32 v192, 0xc000, v192
	s_waitcnt lgkmcnt(0)
	s_barrier
	s_branch .LBB0_1094
.LBB0_1093:
	s_or_b64 exec, exec, s[18:19]
	v_xor_b32_e32 v192, 0xc000, v192
	v_xor_b32_e32 v194, 0xc000, v194
	v_xor_b32_e32 v190, 0xc000, v190
	s_mov_b32 s38, s36
	s_mov_b32 s39, s36
	s_mov_b32 s37, s36
	s_waitcnt vmcnt(0)
	v_mov_b64_e32 v[152:153], s[38:39]
	v_mov_b64_e32 v[150:151], s[36:37]
	v_exp_f32_e32 v161, v96
	v_exp_f32_e32 v196, v97
	v_mfma_f32_32x32x16_bf16 v[32:47], v[80:83], v[150:153], v[32:47]
	v_exp_f32_e32 v158, v98
	v_exp_f32_e32 v168, v99
	v_exp_f32_e32 v159, v100
	v_exp_f32_e32 v169, v101
	v_exp_f32_e32 v160, v102
	v_exp_f32_e32 v195, v103
	v_exp_f32_e32 v154, v105
	v_mfma_f32_32x32x16_bf16 v[32:47], v[84:87], v[150:153], v[32:47]
	v_exp_f32_e32 v155, v107
	v_exp_f32_e32 v156, v109
	v_exp_f32_e32 v157, v111
	s_mov_b64 s[34:35], 0x2000
	s_mov_b64 s[18:19], 0x80000
	v_lshl_add_u64 v[162:163], v[162:163], 0, s[34:35]
	v_lshl_add_u64 v[164:165], v[164:165], 0, s[18:19]
	v_mfma_f32_32x32x16_bf16 v[32:47], v[88:91], v[150:153], v[32:47]
	v_lshl_add_u64 v[166:167], v[166:167], 0, s[34:35]
	s_and_b64 vcc, exec, s[4:5]
	s_waitcnt lgkmcnt(0)
	s_barrier
	v_mfma_f32_32x32x16_bf16 v[32:47], v[92:95], v[150:153], v[32:47]
	v_exp_f32_e32 v150, v104
	v_exp_f32_e32 v151, v106
	v_exp_f32_e32 v152, v108
	v_exp_f32_e32 v153, v110
	s_cbranch_vccnz .LBB0_1100
.LBB0_1094:
	ds_read_b128 v[198:201], v191 offset:36352
	ds_read_b128 v[80:83], v191 offset:29696
	ds_read_b128 v[202:205], v191 offset:29728
	v_exp_f32_e32 v72, v72
	v_exp_f32_e32 v73, v73
	v_exp_f32_e32 v74, v74
	s_waitcnt lgkmcnt(1)
	v_mfma_f32_32x32x16_bf16 v[96:111], v[80:83], v[134:137], v[48:63]
	v_exp_f32_e32 v75, v75
	v_exp_f32_e32 v197, v64
	v_exp_f32_e32 v206, v77
	v_exp_f32_e32 v207, v78
	v_exp_f32_e32 v208, v79
	v_mfma_f32_32x32x16_bf16 v[80:95], v[198:201], v[134:137], v[48:63]
	ds_read_b128 v[198:201], v191 offset:36384
	s_waitcnt lgkmcnt(1)
	v_mfma_f32_32x32x16_bf16 v[96:111], v[202:205], v[130:133], v[96:111]
	s_waitcnt lgkmcnt(0)
	v_mfma_f32_32x32x16_bf16 v[80:95], v[198:201], v[130:133], v[80:95]
	ds_read_b128 v[198:201], v191 offset:29760
	ds_read_b128 v[202:205], v191 offset:36416
	s_waitcnt lgkmcnt(1)
	v_mfma_f32_32x32x16_bf16 v[96:111], v[198:201], v[126:129], v[96:111]
	s_waitcnt lgkmcnt(0)
	v_mfma_f32_32x32x16_bf16 v[80:95], v[202:205], v[126:129], v[80:95]
	ds_read_b128 v[198:201], v191 offset:29792
	ds_read_b128 v[202:205], v191 offset:36448
	s_waitcnt lgkmcnt(1)
	v_mfma_f32_32x32x16_bf16 v[96:111], v[198:201], v[122:125], v[96:111]
	s_waitcnt lgkmcnt(0)
	v_mfma_f32_32x32x16_bf16 v[80:95], v[202:205], v[122:125], v[80:95]
	ds_read_b128 v[198:201], v191 offset:29824
	ds_read_b128 v[202:205], v191 offset:36480
	s_waitcnt lgkmcnt(1)
	v_mfma_f32_32x32x16_bf16 v[96:111], v[198:201], v[118:121], v[96:111]
	s_waitcnt lgkmcnt(0)
	v_mfma_f32_32x32x16_bf16 v[80:95], v[202:205], v[118:121], v[80:95]
	ds_read_b128 v[198:201], v191 offset:29856
	ds_read_b128 v[202:205], v191 offset:36512
	s_waitcnt lgkmcnt(1)
	v_mfma_f32_32x32x16_bf16 v[96:111], v[198:201], v[114:117], v[96:111]
	v_exp_f32_e32 v198, v65
	v_exp_f32_e32 v199, v66
	v_exp_f32_e32 v200, v67
	v_exp_f32_e32 v201, v68
	v_cvt_pk_bf16_f32 v68, v161, v196
	s_waitcnt lgkmcnt(0)
	v_mfma_f32_32x32x16_bf16 v[80:95], v[202:205], v[114:117], v[80:95]
	v_exp_f32_e32 v202, v69
	v_exp_f32_e32 v203, v70
	v_exp_f32_e32 v204, v71
	v_exp_f32_e32 v205, v76
	v_cvt_pk_bf16_f32 v69, v158, v168
	v_cvt_pk_bf16_f32 v70, v159, v169
	v_cvt_pk_bf16_f32 v71, v160, v195
	v_cvt_pk_bf16_f32 v64, v150, v154
	v_cvt_pk_bf16_f32 v65, v151, v155
	v_cvt_pk_bf16_f32 v66, v152, v156
	v_cvt_pk_bf16_f32 v67, v153, v157
	v_cvt_pk_bf16_f32 v76, v197, v198
	v_cvt_pk_bf16_f32 v77, v199, v200
	v_cvt_pk_bf16_f32 v78, v201, v202
	v_cvt_pk_bf16_f32 v79, v203, v204
	v_cvt_pk_bf16_f32 v72, v72, v73
	v_cvt_pk_bf16_f32 v73, v74, v75
	v_cvt_pk_bf16_f32 v74, v205, v206
	v_cvt_pk_bf16_f32 v75, v207, v208
	v_lshl_add_u64 v[168:169], s[26:27], 0, v[164:165]
	s_mov_b32 s4, 0x218c0000
	v_add_co_u32_e32 v150, vcc, s4, v168
	s_nop 1
	v_addc_co_u32_e32 v151, vcc, 0, v169, vcc
	global_load_dwordx4 v[154:157], v[150:151], off offset:128
	global_load_dwordx4 v[158:161], v[150:151], off
	v_lshl_add_u64 v[150:151], s[26:27], 0, v[166:167]
	global_load_dwordx4 v[150:153], v[150:151], off
	ds_read_b64_tr_b16 v[196:197], v194 offset:0
	ds_read_b64_tr_b16 v[198:199], v194 offset:0x400
	ds_read_b64_tr_b16 v[200:201], v194 offset:0x800
	ds_read_b64_tr_b16 v[202:203], v194 offset:0xc00
	ds_read_b64_tr_b16 v[204:205], v194 offset:0x1000
	ds_read_b64_tr_b16 v[206:207], v194 offset:0x1400
	ds_read_b64_tr_b16 v[208:209], v194 offset:0x1800
	ds_read_b64_tr_b16 v[210:211], v194 offset:0x1c00
	s_waitcnt lgkmcnt(0)
; #define SBAR() __builtin_amdgcn_sched_barrier(0)
; #define SLOAD(i, k0) do { st_[i].vs = *reinterpret_cast<const bf16x8*>(&Vh[(size_t)((k0) + sr) * LDK + sc]); \
;     st_[i].ks = *reinterpret_cast<const bf16x8*>(&Kh[(size_t)((k0) + sr) * LDK + sc]); \
;     if (DQ == 96) st_[i].kr = *reinterpret_cast<const bf16x8*>(&Kr[(size_t)((k0) + sr2) * 32 + sc2]); } while (0)
; #define SWRITE(b, i) do { *(bf16x8*)(V_lds + (b) * SHM_V + vst0) = st_[i].vs; *(bf16x8*)(K_lds + (b) * SHM_K + kst0) = st_[i].ks; \
;     if (DQ == 96) { if (tid < 256) *(bf16x8*)(K_lds + (b) * SHM_K + kst2) = st_[i].kr; } } while (0)
; #define SWAIT() do { if (DQ == 96) asm volatile("s_waitcnt vmcnt(3)" ::: "memory"); else asm volatile("s_waitcnt vmcnt(2)" ::: "memory"); } while (0)
; #define SLOAD(i, k0) do { st_[i].vs = *reinterpret_cast<const bf16x8*>(&Vh[(size_t)((k0) + sr) * LDK + sc]); \
;     st_[i].ks = *reinterpret_cast<const bf16x8*>(&Kh[(size_t)((k0) + sr) * LDK + sc]); \
;     if (DQ == 96) st_[i].kr = *reinterpret_cast<const bf16x8*>(&Kr[(size_t)((k0) + sr2) * 32 + sc2]); } while (0)
; #define SWRITE(b, i) do { *(bf16x8*)(V_lds + (b) * SHM_V + vst0) = st_[i].vs; *(bf16x8*)(K_lds + (b) * SHM_K + kst0) = st_[i].ks; \
;     if (DQ == 96) { if (tid < 256) *(bf16x8*)(K_lds + (b) * SHM_K + kst2) = st_[i].kr; } } while (0)
; #define SWAIT() do { if (DQ == 96) asm volatile("s_waitcnt vmcnt(3)" ::: "memory"); else asm volatile("s_waitcnt vmcnt(2)" ::: "memory"); } while (0)
; template <int DQ, bool WIN, int LDQ, int LDK> ...
;     ...
;         pv(vb0);
;         __syncthreads(); SWAIT(); SWRITE(0, SE);
;         lsum_upd();
;         if (WIN) win_mask(pB0, pB1, qrow - KBASE(j), hi);
;         exp16(pB0);
;         __syncthreads();
;         SBAR(); qkt<DQ>(pA0, pA1, K_lds, qr, minit, r32, hi);
;         finish(pB0, pB1); SBAR();
;         if (j + 3 < NT) SLOAD(SE, KBASE(j + 3)); SBAR();
;         pv(vb0 + SHM_V);
;         __syncthreads(); SWAIT(); SWRITE(1, SO);
;         lsum_upd();
	s_nop 0
	v_mfma_f32_32x32x16_bf16 v[0:15], v[68:71], v[196:199], v[0:15]
	ds_read_b64_tr_b16 v[196:197], v194 offset:0x200
	ds_read_b64_tr_b16 v[198:199], v194 offset:0x600
	v_mfma_f32_32x32x16_bf16 v[0:15], v[64:67], v[200:203], v[0:15]
	ds_read_b64_tr_b16 v[200:201], v194 offset:0xa00
	ds_read_b64_tr_b16 v[202:203], v194 offset:0xe00
	v_mfma_f32_32x32x16_bf16 v[0:15], v[76:79], v[204:207], v[0:15]
	ds_read_b64_tr_b16 v[204:205], v194 offset:0x1200
	ds_read_b64_tr_b16 v[206:207], v194 offset:0x1600
	v_mfma_f32_32x32x16_bf16 v[0:15], v[72:75], v[208:211], v[0:15]
	ds_read_b64_tr_b16 v[208:209], v194 offset:0x1a00
	ds_read_b64_tr_b16 v[210:211], v194 offset:0x1e00
	s_waitcnt lgkmcnt(0)
	v_mfma_f32_32x32x16_bf16 v[16:31], v[68:71], v[196:199], v[16:31]
	s_waitcnt vmcnt(3)
	s_waitcnt vmcnt(5)
	ds_write_b128 v192, v[138:141]
	s_waitcnt vmcnt(4)
	ds_write_b128 v193, v[142:145] offset:16384
	v_mfma_f32_32x32x16_bf16 v[16:31], v[64:67], v[200:203], v[16:31]
	v_mfma_f32_32x32x16_bf16 v[16:31], v[76:79], v[204:207], v[16:31]
	v_mfma_f32_32x32x16_bf16 v[16:31], v[72:75], v[208:211], v[16:31]
	s_and_saveexec_b64 s[4:5], s[40:41]
	s_cbranch_execz .LBB0_1096
	s_waitcnt vmcnt(3)
	ds_write_b128 v112, v[146:149] offset:16512
.LBB0_1096:
	s_or_b64 exec, exec, s[4:5]
	s_mov_b32 s38, s36
	s_mov_b32 s39, s36
	s_mov_b32 s37, s36
	v_mov_b64_e32 v[198:199], s[38:39]
	v_mov_b64_e32 v[196:197], s[36:37]
	s_add_i32 s17, s17, 2
	v_exp_f32_e32 v195, v96
	v_mfma_f32_32x32x16_bf16 v[32:47], v[68:71], v[196:199], v[32:47]
	v_exp_f32_e32 v204, v97
	v_exp_f32_e32 v205, v98
	v_exp_f32_e32 v206, v99
	v_exp_f32_e32 v207, v100
	v_exp_f32_e32 v208, v101
	v_exp_f32_e32 v209, v102
	v_exp_f32_e32 v210, v103
	v_mfma_f32_32x32x16_bf16 v[32:47], v[64:67], v[196:199], v[32:47]
	v_exp_f32_e32 v211, v104
	v_exp_f32_e32 v212, v105
	v_exp_f32_e32 v213, v106
	v_exp_f32_e32 v214, v107
	v_exp_f32_e32 v215, v108
	v_exp_f32_e32 v216, v109
	v_exp_f32_e32 v217, v110
	v_mfma_f32_32x32x16_bf16 v[32:47], v[76:79], v[196:199], v[32:47]
	v_exp_f32_e32 v218, v111
	s_waitcnt lgkmcnt(0)
	s_barrier
	v_mfma_f32_32x32x16_bf16 v[32:47], v[72:75], v[196:199], v[32:47]
	ds_read_b128 v[196:199], v191 offset:23040
	ds_read_b128 v[64:67], v191 offset:16384
	ds_read_b128 v[200:203], v191 offset:16416
	v_exp_f32_e32 v95, v95
	v_exp_f32_e32 v219, v88
	v_exp_f32_e32 v220, v89
	s_waitcnt lgkmcnt(1)
	v_mfma_f32_32x32x16_bf16 v[96:111], v[64:67], v[134:137], v[48:63]
	v_exp_f32_e32 v221, v90
	v_exp_f32_e32 v222, v91
	v_exp_f32_e32 v223, v92
	v_exp_f32_e32 v224, v93
	v_exp_f32_e32 v225, v94
	v_mfma_f32_32x32x16_bf16 v[64:79], v[196:199], v[134:137], v[48:63]
	ds_read_b128 v[196:199], v191 offset:23072
	s_waitcnt lgkmcnt(1)
	v_mfma_f32_32x32x16_bf16 v[96:111], v[200:203], v[130:133], v[96:111]
	s_waitcnt lgkmcnt(0)
	v_mfma_f32_32x32x16_bf16 v[64:79], v[196:199], v[130:133], v[64:79]
	ds_read_b128 v[196:199], v191 offset:16448
	ds_read_b128 v[200:203], v191 offset:23104
	s_waitcnt lgkmcnt(1)
	v_mfma_f32_32x32x16_bf16 v[96:111], v[196:199], v[126:129], v[96:111]
	s_waitcnt lgkmcnt(0)
	v_mfma_f32_32x32x16_bf16 v[64:79], v[200:203], v[126:129], v[64:79]
	ds_read_b128 v[196:199], v191 offset:16480
	ds_read_b128 v[200:203], v191 offset:23136
	s_waitcnt lgkmcnt(1)
	v_mfma_f32_32x32x16_bf16 v[96:111], v[196:199], v[122:125], v[96:111]
	s_waitcnt lgkmcnt(0)
	v_mfma_f32_32x32x16_bf16 v[64:79], v[200:203], v[122:125], v[64:79]
	ds_read_b128 v[196:199], v191 offset:16512
	ds_read_b128 v[200:203], v191 offset:23168
	s_waitcnt lgkmcnt(1)
	v_mfma_f32_32x32x16_bf16 v[96:111], v[196:199], v[118:121], v[96:111]
	s_waitcnt lgkmcnt(0)
	v_mfma_f32_32x32x16_bf16 v[64:79], v[200:203], v[118:121], v[64:79]
	ds_read_b128 v[196:199], v191 offset:16544
	ds_read_b128 v[200:203], v191 offset:23200
	s_waitcnt lgkmcnt(1)
	v_mfma_f32_32x32x16_bf16 v[96:111], v[196:199], v[114:117], v[96:111]
	v_exp_f32_e32 v196, v80
	v_exp_f32_e32 v197, v81
	v_exp_f32_e32 v198, v82
	v_exp_f32_e32 v199, v83
	v_cvt_pk_bf16_f32 v80, v195, v204
	v_cvt_pk_bf16_f32 v81, v205, v206
	v_cvt_pk_bf16_f32 v82, v207, v208
	s_waitcnt lgkmcnt(0)
	v_mfma_f32_32x32x16_bf16 v[64:79], v[200:203], v[114:117], v[64:79]
	v_exp_f32_e32 v200, v84
	v_exp_f32_e32 v201, v85
	v_exp_f32_e32 v202, v86
	v_exp_f32_e32 v203, v87
	v_cvt_pk_bf16_f32 v83, v209, v210
	v_cvt_pk_bf16_f32 v84, v211, v212
	v_cvt_pk_bf16_f32 v85, v213, v214
	v_cvt_pk_bf16_f32 v86, v215, v216
	v_cvt_pk_bf16_f32 v87, v217, v218
	v_cvt_pk_bf16_f32 v88, v196, v197
	v_cvt_pk_bf16_f32 v89, v198, v199
	v_cvt_pk_bf16_f32 v90, v200, v201
	v_cvt_pk_bf16_f32 v91, v202, v203
	v_cvt_pk_bf16_f32 v92, v219, v220
	v_cvt_pk_bf16_f32 v93, v221, v222
	v_cvt_pk_bf16_f32 v94, v223, v224
	v_cvt_pk_bf16_f32 v95, v225, v95
	s_cmpk_gt_u32 s17, 0x7c
	s_cselect_b64 s[4:5], -1, 0
	s_and_b64 vcc, exec, s[4:5]
	s_cbranch_vccnz .LBB0_1098
	v_add_co_u32_e32 v142, vcc, 0x21900000, v168
	s_waitcnt vmcnt(3)
	v_lshl_add_u64 v[146:147], s[26:27], 0, v[162:163]
	v_addc_co_u32_e32 v143, vcc, 0, v169, vcc
	global_load_dwordx4 v[138:141], v[142:143], off offset:128
	s_nop 0
	global_load_dwordx4 v[142:145], v[142:143], off
	s_nop 0
	global_load_dwordx4 v[146:149], v[146:147], off
; #define SBAR() __builtin_amdgcn_sched_barrier(0)
; #define SWRITE(b, i) do { *(bf16x8*)(V_lds + (b) * SHM_V + vst0) = st_[i].vs; *(bf16x8*)(K_lds + (b) * SHM_K + kst0) = st_[i].ks; \
;     if (DQ == 96) { if (tid < 256) *(bf16x8*)(K_lds + (b) * SHM_K + kst2) = st_[i].kr; } } while (0)
; #define SWAIT() do { if (DQ == 96) asm volatile("s_waitcnt vmcnt(3)" ::: "memory"); else asm volatile("s_waitcnt vmcnt(2)" ::: "memory"); } while (0)
; #define SWRITE(b, i) do { *(bf16x8*)(V_lds + (b) * SHM_V + vst0) = st_[i].vs; *(bf16x8*)(K_lds + (b) * SHM_K + kst0) = st_[i].ks; \
;     if (DQ == 96) { if (tid < 256) *(bf16x8*)(K_lds + (b) * SHM_K + kst2) = st_[i].kr; } } while (0)
; #define SWAIT() do { if (DQ == 96) asm volatile("s_waitcnt vmcnt(3)" ::: "memory"); else asm volatile("s_waitcnt vmcnt(2)" ::: "memory"); } while (0)
; template <int DQ, bool WIN, int LDQ, int LDK> ...
;     ...
;         pv(vb0 + SHM_V);
;         __syncthreads(); SWAIT(); SWRITE(1, SO);
;         lsum_upd();
;         if (WIN) win_mask(pA0, pA1, qrow - KBASE(j + 1), hi);
;         exp16(pA0);
;         __syncthreads();
;     }
;     SBAR(); qkt<DQ>(pB0, pB1, K_lds + SHM_K, qr, minit, r32, hi);
;     finish(pA0, pA1); SBAR();
;     pv(vb0); lsum_upd();
;     if (WIN) win_mask(pB0, pB1, qrow - KBASE(NT - 1), hi);
;     exp16(pB0);
;     finish(pB0, pB1); SBAR();
;     pv(vb0 + SHM_V); lsum_upd();
.LBB0_1098:
	ds_read_b64_tr_b16 v[196:197], v190 offset:0
	ds_read_b64_tr_b16 v[198:199], v190 offset:0x400
	ds_read_b64_tr_b16 v[200:201], v190 offset:0x800
	ds_read_b64_tr_b16 v[202:203], v190 offset:0xc00
	ds_read_b64_tr_b16 v[204:205], v190 offset:0x1000
	ds_read_b64_tr_b16 v[206:207], v190 offset:0x1400
	ds_read_b64_tr_b16 v[208:209], v190 offset:0x1800
	ds_read_b64_tr_b16 v[210:211], v190 offset:0x1c00
	s_waitcnt lgkmcnt(0)
	s_nop 0
	v_mfma_f32_32x32x16_bf16 v[0:15], v[80:83], v[196:199], v[0:15]
	ds_read_b64_tr_b16 v[196:197], v190 offset:0x200
	ds_read_b64_tr_b16 v[198:199], v190 offset:0x600
	v_mfma_f32_32x32x16_bf16 v[0:15], v[84:87], v[200:203], v[0:15]
	ds_read_b64_tr_b16 v[200:201], v190 offset:0xa00
	ds_read_b64_tr_b16 v[202:203], v190 offset:0xe00
	v_mfma_f32_32x32x16_bf16 v[0:15], v[88:91], v[204:207], v[0:15]
	ds_read_b64_tr_b16 v[204:205], v190 offset:0x1200
	ds_read_b64_tr_b16 v[206:207], v190 offset:0x1600
	v_mfma_f32_32x32x16_bf16 v[0:15], v[92:95], v[208:211], v[0:15]
	ds_read_b64_tr_b16 v[208:209], v190 offset:0x1a00
	ds_read_b64_tr_b16 v[210:211], v190 offset:0x1e00
	s_waitcnt lgkmcnt(0)
	v_mfma_f32_32x32x16_bf16 v[16:31], v[80:83], v[196:199], v[16:31]
	s_waitcnt vmcnt(3)
	s_waitcnt vmcnt(2)
	ds_write_b128 v192, v[154:157] offset:8192
	s_waitcnt vmcnt(1)
	ds_write_b128 v193, v[158:161] offset:29696
	v_mfma_f32_32x32x16_bf16 v[16:31], v[84:87], v[200:203], v[16:31]
	v_mfma_f32_32x32x16_bf16 v[16:31], v[88:91], v[204:207], v[16:31]
	v_mfma_f32_32x32x16_bf16 v[16:31], v[92:95], v[208:211], v[16:31]
	s_and_saveexec_b64 s[18:19], s[40:41]
	s_cbranch_execz .LBB0_1093
	s_waitcnt vmcnt(0)
	ds_write_b128 v112, v[150:153] offset:29824
	s_branch .LBB0_1093
.LBB0_1100:
	ds_read_b128 v[96:99], v191 offset:29696
	v_exp_f32_e32 v79, v79
	v_exp_f32_e32 v112, v64
	s_waitcnt lgkmcnt(0)
	v_mfma_f32_32x32x16_bf16 v[80:95], v[96:99], v[134:137], v[48:63]
	ds_read_b128 v[96:99], v191 offset:36352
	s_waitcnt lgkmcnt(0)
	v_mfma_f32_32x32x16_bf16 v[48:63], v[96:99], v[134:137], v[48:63]
	ds_read_b128 v[96:99], v191 offset:29728
	s_waitcnt lgkmcnt(0)
	v_mfma_f32_32x32x16_bf16 v[80:95], v[96:99], v[130:133], v[80:95]
	ds_read_b128 v[96:99], v191 offset:36384
	s_waitcnt lgkmcnt(0)
	v_mfma_f32_32x32x16_bf16 v[48:63], v[96:99], v[130:133], v[48:63]
	ds_read_b128 v[96:99], v191 offset:29760
	v_exp_f32_e32 v130, v65
	v_exp_f32_e32 v131, v66
	s_waitcnt lgkmcnt(0)
	v_mfma_f32_32x32x16_bf16 v[80:95], v[96:99], v[126:129], v[80:95]
	ds_read_b128 v[96:99], v191 offset:36416
	s_waitcnt lgkmcnt(0)
	v_mfma_f32_32x32x16_bf16 v[48:63], v[96:99], v[126:129], v[48:63]
	ds_read_b128 v[96:99], v191 offset:29792
	ds_read_b128 v[100:103], v191 offset:36448
	s_waitcnt lgkmcnt(1)
	v_mfma_f32_32x32x16_bf16 v[80:95], v[96:99], v[122:125], v[80:95]
	ds_read_b128 v[96:99], v191 offset:29824
	ds_read_b128 v[104:107], v191 offset:29856
	ds_read_b128 v[108:111], v191 offset:36480
	ds_read_b128 v[126:129], v191 offset:36512
	v_cvt_pk_bf16_f32 v64, v161, v196
	v_cvt_pk_bf16_f32 v65, v158, v168
	v_cvt_pk_bf16_f32 v66, v159, v169
	s_waitcnt lgkmcnt(4)
	v_mfma_f32_32x32x16_bf16 v[48:63], v[100:103], v[122:125], v[48:63]
	v_exp_f32_e32 v100, v67
	v_exp_f32_e32 v101, v68
	v_exp_f32_e32 v102, v69
	v_exp_f32_e32 v103, v70
	v_exp_f32_e32 v122, v71
	v_exp_f32_e32 v123, v72
	v_exp_f32_e32 v124, v73
	s_waitcnt lgkmcnt(3)
	v_mfma_f32_32x32x16_bf16 v[80:95], v[96:99], v[118:121], v[80:95]
	v_exp_f32_e32 v96, v74
	v_exp_f32_e32 v97, v75
	v_exp_f32_e32 v98, v76
	v_exp_f32_e32 v99, v77
	v_exp_f32_e32 v125, v78
	v_cvt_pk_bf16_f32 v67, v160, v195
	v_cvt_pk_bf16_f32 v68, v150, v154
	s_waitcnt lgkmcnt(1)
	v_mfma_f32_32x32x16_bf16 v[48:63], v[108:111], v[118:121], v[48:63]
	v_cvt_pk_bf16_f32 v69, v151, v155
	v_cvt_pk_bf16_f32 v70, v152, v156
	v_cvt_pk_bf16_f32 v71, v153, v157
	v_cvt_pk_bf16_f32 v72, v112, v130
	v_cvt_pk_bf16_f32 v73, v131, v100
	v_cvt_pk_bf16_f32 v74, v101, v102
	v_cvt_pk_bf16_f32 v75, v103, v122
	v_mfma_f32_32x32x16_bf16 v[80:95], v[104:107], v[114:117], v[80:95]
	v_cvt_pk_bf16_f32 v76, v123, v124
	v_cvt_pk_bf16_f32 v77, v96, v97
	v_cvt_pk_bf16_f32 v78, v98, v99
	v_cvt_pk_bf16_f32 v79, v125, v79
	s_waitcnt lgkmcnt(0)
	v_mfma_f32_32x32x16_bf16 v[48:63], v[126:129], v[114:117], v[48:63]
	ds_read_b64_tr_b16 v[96:97], v194 offset:0
	ds_read_b64_tr_b16 v[98:99], v194 offset:0x400
	ds_read_b64_tr_b16 v[100:101], v194 offset:0x800
	ds_read_b64_tr_b16 v[102:103], v194 offset:0xc00
	ds_read_b64_tr_b16 v[104:105], v194 offset:0x1000
	ds_read_b64_tr_b16 v[106:107], v194 offset:0x1400
	ds_read_b64_tr_b16 v[108:109], v194 offset:0x1800
	ds_read_b64_tr_b16 v[110:111], v194 offset:0x1c00
	s_waitcnt lgkmcnt(0)
	s_nop 0
	v_mfma_f32_32x32x16_bf16 v[0:15], v[64:67], v[96:99], v[0:15]
	ds_read_b64_tr_b16 v[96:97], v194 offset:0x200
	ds_read_b64_tr_b16 v[98:99], v194 offset:0x600
	v_mfma_f32_32x32x16_bf16 v[0:15], v[68:71], v[100:103], v[0:15]
	ds_read_b64_tr_b16 v[100:101], v194 offset:0xa00
	ds_read_b64_tr_b16 v[102:103], v194 offset:0xe00
	v_mfma_f32_32x32x16_bf16 v[0:15], v[72:75], v[104:107], v[0:15]
	ds_read_b64_tr_b16 v[104:105], v194 offset:0x1200
	ds_read_b64_tr_b16 v[106:107], v194 offset:0x1600
	v_mfma_f32_32x32x16_bf16 v[0:15], v[76:79], v[108:111], v[0:15]
	ds_read_b64_tr_b16 v[108:109], v194 offset:0x1a00
	ds_read_b64_tr_b16 v[110:111], v194 offset:0x1e00
	s_waitcnt lgkmcnt(0)
; #define SBAR() __builtin_amdgcn_sched_barrier(0)
; __device__ __forceinline__ int crow(int r, int hi) { return (r & 3) + 8 * (r >> 2) + 4 * hi; }
; template <int DQ, bool WIN, int LDQ, int LDK> ...
;     ...
;     finish(pB0, pB1); SBAR();
;     pv(vb0 + SHM_V); lsum_upd();
;     if (WIN) {
;         if (hi == 0) li_l[r32] = m_ref; asm volatile("s_waitcnt lgkmcnt(0)" ::: "memory");
; #pragma unroll
;         for (int r = 0; r < 16; ++r) lsum[r] += __builtin_amdgcn_exp2f(sink_l2 - li_l[crow(r, hi)]);
;     }
;     float rli[16]; bool fin = true;
; #pragma unroll
;     for (int r = 0; r < 16; ++r) { fin = fin && (lsum[r] < ATT_GUARD) && (lsum[r] > 0.f); rli[r] = __builtin_amdgcn_rcpf(lsum[r]); }
;     if (!__all(fin)) { if (lane == 0) *redo_flag = 1; }
	v_mfma_f32_32x32x16_bf16 v[16:31], v[64:67], v[96:99], v[16:31]
	v_mov_b64_e32 v[98:99], s[38:39]
	v_mov_b64_e32 v[96:97], s[36:37]
	s_nop 3
	v_exp_f32_e32 v63, v63
	v_mfma_f32_32x32x16_bf16 v[32:47], v[64:67], v[96:99], v[32:47]
	v_exp_f32_e32 v64, v80
	v_exp_f32_e32 v65, v81
	v_exp_f32_e32 v66, v82
	v_exp_f32_e32 v67, v83
	v_exp_f32_e32 v80, v48
	v_exp_f32_e32 v81, v49
	v_exp_f32_e32 v82, v50
	v_mfma_f32_32x32x16_bf16 v[16:31], v[68:71], v[100:103], v[16:31]
	v_exp_f32_e32 v83, v51
	v_cvt_pk_bf16_f32 v48, v64, v65
	v_cvt_pk_bf16_f32 v49, v66, v67
	v_mfma_f32_32x32x16_bf16 v[32:47], v[68:71], v[96:99], v[32:47]
	v_exp_f32_e32 v68, v84
	v_exp_f32_e32 v69, v85
	v_exp_f32_e32 v70, v86
	v_exp_f32_e32 v71, v87
	v_exp_f32_e32 v84, v52
	v_exp_f32_e32 v85, v53
	v_exp_f32_e32 v86, v54
	v_mfma_f32_32x32x16_bf16 v[16:31], v[72:75], v[104:107], v[16:31]
	v_exp_f32_e32 v87, v55
	v_cvt_pk_bf16_f32 v50, v68, v69
	v_cvt_pk_bf16_f32 v51, v70, v71
	v_mfma_f32_32x32x16_bf16 v[32:47], v[72:75], v[96:99], v[32:47]
	v_exp_f32_e32 v72, v88
	v_exp_f32_e32 v73, v89
	v_exp_f32_e32 v74, v90
	v_exp_f32_e32 v75, v91
	v_exp_f32_e32 v88, v56
	v_exp_f32_e32 v89, v57
	v_exp_f32_e32 v90, v58
	v_mfma_f32_32x32x16_bf16 v[16:31], v[76:79], v[108:111], v[16:31]
	v_exp_f32_e32 v91, v59
	v_cvt_pk_bf16_f32 v52, v72, v73
	v_cvt_pk_bf16_f32 v53, v74, v75
	v_mfma_f32_32x32x16_bf16 v[32:47], v[76:79], v[96:99], v[32:47]
	v_exp_f32_e32 v76, v92
	v_exp_f32_e32 v77, v93
	v_exp_f32_e32 v78, v94
	v_exp_f32_e32 v79, v95
	v_exp_f32_e32 v92, v60
	v_exp_f32_e32 v93, v61
	v_exp_f32_e32 v94, v62
	v_cvt_pk_bf16_f32 v54, v76, v77
	v_cvt_pk_bf16_f32 v55, v78, v79
	v_cvt_pk_bf16_f32 v56, v80, v81
	v_cvt_pk_bf16_f32 v57, v82, v83
	v_cvt_pk_bf16_f32 v58, v84, v85
	v_cvt_pk_bf16_f32 v59, v86, v87
	v_cvt_pk_bf16_f32 v60, v88, v89
	v_cvt_pk_bf16_f32 v61, v90, v91
	v_cvt_pk_bf16_f32 v62, v92, v93
	v_cvt_pk_bf16_f32 v63, v94, v63
	ds_read_b64_tr_b16 v[64:65], v190 offset:0
	ds_read_b64_tr_b16 v[66:67], v190 offset:0x400
	ds_read_b64_tr_b16 v[68:69], v190 offset:0x800
	ds_read_b64_tr_b16 v[70:71], v190 offset:0xc00
	ds_read_b64_tr_b16 v[72:73], v190 offset:0x1000
	ds_read_b64_tr_b16 v[74:75], v190 offset:0x1400
	ds_read_b64_tr_b16 v[76:77], v190 offset:0x1800
	ds_read_b64_tr_b16 v[78:79], v190 offset:0x1c00
	s_waitcnt lgkmcnt(0)
	s_nop 0
	v_mfma_f32_32x32x16_bf16 v[0:15], v[48:51], v[64:67], v[0:15]
	ds_read_b64_tr_b16 v[64:65], v190 offset:0x200
	ds_read_b64_tr_b16 v[66:67], v190 offset:0x600
	v_mfma_f32_32x32x16_bf16 v[0:15], v[52:55], v[68:71], v[0:15]
	ds_read_b64_tr_b16 v[68:69], v190 offset:0xa00
	ds_read_b64_tr_b16 v[70:71], v190 offset:0xe00
	v_mfma_f32_32x32x16_bf16 v[0:15], v[56:59], v[72:75], v[0:15]
	ds_read_b64_tr_b16 v[72:73], v190 offset:0x1200
	ds_read_b64_tr_b16 v[74:75], v190 offset:0x1600
	v_mfma_f32_32x32x16_bf16 v[0:15], v[60:63], v[76:79], v[0:15]
	ds_read_b64_tr_b16 v[76:77], v190 offset:0x1a00
	ds_read_b64_tr_b16 v[78:79], v190 offset:0x1e00
	s_waitcnt lgkmcnt(0)
	v_mfma_f32_32x32x16_bf16 v[32:47], v[48:51], v[96:99], v[32:47]
	s_mov_b32 s17, 0x7149f2ca
	v_mfma_f32_32x32x16_bf16 v[32:47], v[52:55], v[96:99], v[32:47]
	v_mfma_f32_32x32x16_bf16 v[32:47], v[56:59], v[96:99], v[32:47]
	v_mfma_f32_32x32x16_bf16 v[32:47], v[60:63], v[96:99], v[32:47]
	v_mfma_f32_32x32x16_bf16 v[16:31], v[48:51], v[64:67], v[16:31]
	s_nop 10
	v_cmp_gt_f32_e32 vcc, s17, v32
	v_cmp_lt_f32_e64 s[4:5], 0, v32
	s_and_b64 s[18:19], vcc, s[4:5]
	v_cmp_gt_f32_e32 vcc, s17, v33
	v_cmp_lt_f32_e64 s[4:5], 0, v33
	s_and_b64 s[4:5], vcc, s[4:5]
	s_and_b64 s[18:19], s[18:19], s[4:5]
	v_cmp_gt_f32_e32 vcc, s17, v34
	v_cmp_lt_f32_e64 s[4:5], 0, v34
	s_and_b64 s[4:5], vcc, s[4:5]
	s_and_b64 s[18:19], s[18:19], s[4:5]
	v_cmp_gt_f32_e32 vcc, s17, v35
	v_cmp_lt_f32_e64 s[4:5], 0, v35
	s_and_b64 s[4:5], vcc, s[4:5]
	s_and_b64 s[18:19], s[18:19], s[4:5]
	v_cmp_gt_f32_e32 vcc, s17, v36
	v_cmp_lt_f32_e64 s[4:5], 0, v36
	s_and_b64 s[4:5], vcc, s[4:5]
	s_and_b64 s[18:19], s[18:19], s[4:5]
	v_cmp_gt_f32_e32 vcc, s17, v37
	v_cmp_lt_f32_e64 s[4:5], 0, v37
	s_and_b64 s[4:5], vcc, s[4:5]
	s_and_b64 s[18:19], s[18:19], s[4:5]
	v_cmp_gt_f32_e32 vcc, s17, v38
	v_cmp_lt_f32_e64 s[4:5], 0, v38
	s_and_b64 s[4:5], vcc, s[4:5]
	s_and_b64 s[18:19], s[18:19], s[4:5]
	v_cmp_gt_f32_e32 vcc, s17, v39
	v_cmp_lt_f32_e64 s[4:5], 0, v39
	s_and_b64 s[4:5], vcc, s[4:5]
	v_mfma_f32_32x32x16_bf16 v[16:31], v[52:55], v[68:71], v[16:31]
	s_and_b64 s[18:19], s[18:19], s[4:5]
	v_cmp_gt_f32_e32 vcc, s17, v40
	v_cmp_lt_f32_e64 s[4:5], 0, v40
	s_and_b64 s[4:5], vcc, s[4:5]
	s_and_b64 s[18:19], s[18:19], s[4:5]
	v_cmp_gt_f32_e32 vcc, s17, v41
	v_cmp_lt_f32_e64 s[4:5], 0, v41
	s_and_b64 s[4:5], vcc, s[4:5]
	s_and_b64 s[18:19], s[18:19], s[4:5]
	v_cmp_gt_f32_e32 vcc, s17, v42
	v_cmp_lt_f32_e64 s[4:5], 0, v42
	s_and_b64 s[4:5], vcc, s[4:5]
	s_and_b64 s[18:19], s[18:19], s[4:5]
	v_cmp_gt_f32_e32 vcc, s17, v43
	v_cmp_lt_f32_e64 s[4:5], 0, v43
	s_and_b64 s[4:5], vcc, s[4:5]
	v_mfma_f32_32x32x16_bf16 v[16:31], v[56:59], v[72:75], v[16:31]
	s_and_b64 s[18:19], s[18:19], s[4:5]
	v_cmp_gt_f32_e32 vcc, s17, v44
	v_cmp_lt_f32_e64 s[4:5], 0, v44
	s_and_b64 s[4:5], vcc, s[4:5]
	s_and_b64 s[18:19], s[18:19], s[4:5]
	v_cmp_gt_f32_e32 vcc, s17, v45
	v_cmp_lt_f32_e64 s[4:5], 0, v45
	s_and_b64 s[4:5], vcc, s[4:5]
	s_and_b64 s[18:19], s[18:19], s[4:5]
	v_cmp_gt_f32_e32 vcc, s17, v46
	v_cmp_lt_f32_e64 s[4:5], 0, v46
	s_and_b64 s[4:5], vcc, s[4:5]
	s_and_b64 s[18:19], s[18:19], s[4:5]
	v_cmp_gt_f32_e32 vcc, s17, v47
	v_cmp_lt_f32_e64 s[4:5], 0, v47
	s_and_b64 s[4:5], vcc, s[4:5]
	v_mfma_f32_32x32x16_bf16 v[16:31], v[60:63], v[76:79], v[16:31]
	s_and_b64 s[4:5], s[18:19], s[4:5]
	v_cndmask_b32_e64 v48, 0, 1, s[4:5]
	v_cmp_ne_u32_e32 vcc, 0, v48
	s_cmp_eq_u64 vcc, exec
	s_cselect_b64 s[4:5], -1, 0
	v_cndmask_b32_e64 v48, 0, 1, s[4:5]
	v_or_b32_e32 v48, v189, v48
	v_cmp_eq_u32_e32 vcc, 0, v48
	s_and_saveexec_b64 s[4:5], vcc
	s_cbranch_execz .LBB0_1102
	s_add_i32 s17, 0, 0xb000
	s_mov_b64 s[18:19], src_shared_base
	s_cmp_lg_u32 s17, -1
	s_cselect_b32 s17, s17, 0
	s_cselect_b32 s18, s19, 0
	v_mov_b32_e32 v48, s17
	v_mov_b32_e32 v49, s18
	flat_store_dword v[48:49], v170 sc0 sc1
	s_waitcnt vmcnt(0)
